# stack + conv pass sample items: state and u-row loads of staging chunks 0-3 in flight together, conversion and LDS stores after one wait
# baseline (speedup 1.0000x reference)
.LBB0_839:
	s_and_saveexec_b64 s[52:53], s[4:5]
	s_xor_b64 s[52:53], exec, s[52:53]
	s_cbranch_execz .LBB0_843
	v_mov_b32_e32 v207, 0
	v_mov_b32_e32 v206, 0
	v_mov_b32_e32 v205, 0
	v_mov_b32_e32 v204, 0
	s_and_saveexec_b64 s[54:55], s[6:7]
	s_cbranch_execz .LBB0_842
	v_add_u32_e32 v204, s75, v20
	v_subrev_u32_e32 v16, 30, v204
	v_lshlrev_b64 v[204:205], 10, v[16:17]
	v_lshl_add_u64 v[204:205], v[18:19], 0, v[204:205]
	global_load_dwordx4 v[204:207], v[204:205], off

.LBB0_843:
	s_andn2_saveexec_b64 s[52:53], s[52:53]
	s_cbranch_execz .LBB0_845
	v_lshl_add_u64 v[204:205], s[0:1], 0, v[20:21]
	v_lshlrev_b64 v[204:205], 11, v[204:205]
	v_lshl_add_u64 v[208:209], v[22:23], 0, v[204:205]
	global_load_dwordx4 v[204:207], v[208:209], off
	s_nop 0
	global_load_dwordx4 v[208:211], v[208:209], off offset:16
.LBB0_845:
	s_or_b64 exec, exec, s[52:53]
	s_or_b64 exec, exec, s[12:13]
	s_and_saveexec_b64 s[12:13], s[8:9]
	s_cbranch_execz .LBB0_833
.LBB0_846:
	s_and_saveexec_b64 s[52:53], s[10:11]
	s_xor_b64 s[52:53], exec, s[52:53]
	s_cbranch_execz .LBB0_850
	v_mov_b32_e32 v215, 0
	v_mov_b32_e32 v214, 0
	v_mov_b32_e32 v213, 0
	v_mov_b32_e32 v212, 0
	s_and_saveexec_b64 s[54:55], s[68:69]
	s_cbranch_execz .LBB0_849
	v_add_u32_e32 v212, s75, v24
	v_subrev_u32_e32 v16, 30, v212
	v_lshlrev_b64 v[212:213], 10, v[16:17]
	v_lshl_add_u64 v[212:213], v[18:19], 0, v[212:213]
	global_load_dwordx4 v[212:215], v[212:213], off

.LBB0_850:
	s_andn2_saveexec_b64 s[52:53], s[52:53]
	s_cbranch_execz .LBB0_852
	v_lshl_add_u64 v[212:213], s[0:1], 0, v[24:25]
	v_lshlrev_b64 v[212:213], 11, v[212:213]
	v_lshl_add_u64 v[216:217], v[22:23], 0, v[212:213]
	global_load_dwordx4 v[212:215], v[216:217], off
	s_nop 0
	global_load_dwordx4 v[216:219], v[216:217], off offset:16
.LBB0_852:
	s_or_b64 exec, exec, s[52:53]
	s_or_b64 exec, exec, s[12:13]
	s_and_saveexec_b64 s[12:13], s[14:15]
	s_cbranch_execz .LBB0_834
.LBB0_853:
	s_and_saveexec_b64 s[52:53], s[16:17]
	s_xor_b64 s[52:53], exec, s[52:53]
	s_cbranch_execz .LBB0_857
	v_mov_b32_e32 v223, 0
	v_mov_b32_e32 v222, 0
	v_mov_b32_e32 v221, 0
	v_mov_b32_e32 v220, 0
	s_and_saveexec_b64 s[54:55], s[18:19]
	s_cbranch_execz .LBB0_856
	v_add_u32_e32 v220, s75, v26
	v_subrev_u32_e32 v16, 30, v220
	v_lshlrev_b64 v[220:221], 10, v[16:17]
	v_lshl_add_u64 v[220:221], v[18:19], 0, v[220:221]
	global_load_dwordx4 v[220:223], v[220:221], off

.LBB0_857:
	s_andn2_saveexec_b64 s[52:53], s[52:53]
	s_cbranch_execz .LBB0_859
	v_lshl_add_u64 v[220:221], s[0:1], 0, v[26:27]
	v_lshlrev_b64 v[220:221], 11, v[220:221]
	v_lshl_add_u64 v[224:225], v[22:23], 0, v[220:221]
	global_load_dwordx4 v[220:223], v[224:225], off
	s_nop 0
	global_load_dwordx4 v[224:227], v[224:225], off offset:16
.LBB0_859:
	s_or_b64 exec, exec, s[52:53]
	s_or_b64 exec, exec, s[12:13]
	s_and_saveexec_b64 s[12:13], s[20:21]
	s_cbranch_execz .LBB0_835
.LBB0_860:
	s_and_saveexec_b64 s[52:53], s[22:23]
	s_xor_b64 s[52:53], exec, s[52:53]
	s_cbranch_execz .LBB0_864
	v_mov_b32_e32 v231, 0
	v_mov_b32_e32 v230, 0
	v_mov_b32_e32 v229, 0
	v_mov_b32_e32 v228, 0
	s_and_saveexec_b64 s[54:55], s[24:25]
	s_cbranch_execz .LBB0_863
	v_add_u32_e32 v228, s75, v28
	v_subrev_u32_e32 v16, 30, v228
	v_lshlrev_b64 v[228:229], 10, v[16:17]
	v_lshl_add_u64 v[228:229], v[18:19], 0, v[228:229]
	global_load_dwordx4 v[228:231], v[228:229], off

.LBB0_864:
	s_andn2_saveexec_b64 s[52:53], s[52:53]
	s_cbranch_execz .LBB0_866
	v_lshl_add_u64 v[228:229], s[0:1], 0, v[28:29]
	v_lshlrev_b64 v[228:229], 11, v[228:229]
	v_lshl_add_u64 v[232:233], v[22:23], 0, v[228:229]
	global_load_dwordx4 v[228:231], v[232:233], off
	s_nop 0
	global_load_dwordx4 v[232:235], v[232:233], off offset:16
.LBB0_866:
	s_or_b64 exec, exec, s[52:53]
	s_or_b64 exec, exec, s[12:13]
	s_and_saveexec_b64 s[12:13], s[26:27]
	s_cbranch_execz .LBB0_836

.LBB0_895:
	s_or_b64 exec, exec, s[12:13]
	s_waitcnt vmcnt(0)
	s_and_saveexec_b64 s[12:13], s[2:3]
	s_andn2_b64 exec, exec, s[4:5]
	v_bfe_u32 v8, v204, 16, 1
	v_bfe_u32 v10, v206, 16, 1
	v_bfe_u32 v12, v208, 16, 1
	v_bfe_u32 v14, v210, 16, 1
	v_bfe_u32 v9, v205, 16, 1
	v_bfe_u32 v11, v207, 16, 1
	v_bfe_u32 v13, v209, 16, 1
	v_bfe_u32 v15, v211, 16, 1
	v_add3_u32 v204, v204, v8, s79
	v_add3_u32 v206, v206, v10, s79
	v_add3_u32 v208, v208, v12, s79
	v_add3_u32 v210, v210, v14, s79
	v_add3_u32 v205, v205, v9, s79
	v_add3_u32 v207, v207, v11, s79
	v_add3_u32 v209, v209, v13, s79
	v_add3_u32 v211, v211, v15, s79
	v_lshrrev_b32_e32 v204, 16, v204
	v_lshrrev_b32_e32 v206, 16, v206
	v_lshrrev_b32_e32 v208, 16, v208
	v_lshrrev_b32_e32 v210, 16, v210
	v_and_or_b32 v204, v205, s80, v204
	v_and_or_b32 v205, v207, s80, v206
	v_and_or_b32 v206, v209, s80, v208
	v_and_or_b32 v207, v211, s80, v210
	s_and_b64 exec, s[12:13], s[2:3]
	v_add_u32_e32 v4, v106, v107
	ds_write_b128 v4, v[204:207]
	s_mov_b64 exec, s[12:13]
	s_and_saveexec_b64 s[12:13], s[8:9]
	s_andn2_b64 exec, exec, s[10:11]
	v_bfe_u32 v8, v212, 16, 1
	v_bfe_u32 v10, v214, 16, 1
	v_bfe_u32 v12, v216, 16, 1
	v_bfe_u32 v14, v218, 16, 1
	v_bfe_u32 v9, v213, 16, 1
	v_bfe_u32 v11, v215, 16, 1
	v_bfe_u32 v13, v217, 16, 1
	v_bfe_u32 v15, v219, 16, 1
	v_add3_u32 v212, v212, v8, s79
	v_add3_u32 v214, v214, v10, s79
	v_add3_u32 v216, v216, v12, s79
	v_add3_u32 v218, v218, v14, s79
	v_add3_u32 v213, v213, v9, s79
	v_add3_u32 v215, v215, v11, s79
	v_add3_u32 v217, v217, v13, s79
	v_add3_u32 v219, v219, v15, s79
	v_lshrrev_b32_e32 v212, 16, v212
	v_lshrrev_b32_e32 v214, 16, v214
	v_lshrrev_b32_e32 v216, 16, v216
	v_lshrrev_b32_e32 v218, 16, v218
	v_and_or_b32 v212, v213, s80, v212
	v_and_or_b32 v213, v215, s80, v214
	v_and_or_b32 v214, v217, s80, v216
	v_and_or_b32 v215, v219, s80, v218
	s_and_b64 exec, s[12:13], s[8:9]
	v_add_u32_e32 v4, v106, v108
	ds_write_b128 v4, v[212:215]
	s_mov_b64 exec, s[12:13]
	s_and_saveexec_b64 s[12:13], s[14:15]
	s_andn2_b64 exec, exec, s[16:17]
	v_bfe_u32 v8, v220, 16, 1
	v_bfe_u32 v10, v222, 16, 1
	v_bfe_u32 v12, v224, 16, 1
	v_bfe_u32 v14, v226, 16, 1
	v_bfe_u32 v9, v221, 16, 1
	v_bfe_u32 v11, v223, 16, 1
	v_bfe_u32 v13, v225, 16, 1
	v_bfe_u32 v15, v227, 16, 1
	v_add3_u32 v220, v220, v8, s79
	v_add3_u32 v222, v222, v10, s79
	v_add3_u32 v224, v224, v12, s79
	v_add3_u32 v226, v226, v14, s79
	v_add3_u32 v221, v221, v9, s79
	v_add3_u32 v223, v223, v11, s79
	v_add3_u32 v225, v225, v13, s79
	v_add3_u32 v227, v227, v15, s79
	v_lshrrev_b32_e32 v220, 16, v220
	v_lshrrev_b32_e32 v222, 16, v222
	v_lshrrev_b32_e32 v224, 16, v224
	v_lshrrev_b32_e32 v226, 16, v226
	v_and_or_b32 v220, v221, s80, v220
	v_and_or_b32 v221, v223, s80, v222
	v_and_or_b32 v222, v225, s80, v224
	v_and_or_b32 v223, v227, s80, v226
	s_and_b64 exec, s[12:13], s[14:15]
	v_add_u32_e32 v4, v106, v109
	ds_write_b128 v4, v[220:223]
	s_mov_b64 exec, s[12:13]
	s_and_saveexec_b64 s[12:13], s[20:21]
	s_andn2_b64 exec, exec, s[22:23]
	v_bfe_u32 v8, v228, 16, 1
	v_bfe_u32 v10, v230, 16, 1
	v_bfe_u32 v12, v232, 16, 1
	v_bfe_u32 v14, v234, 16, 1
	v_bfe_u32 v9, v229, 16, 1
	v_bfe_u32 v11, v231, 16, 1
	v_bfe_u32 v13, v233, 16, 1
	v_bfe_u32 v15, v235, 16, 1
	v_add3_u32 v228, v228, v8, s79
	v_add3_u32 v230, v230, v10, s79
	v_add3_u32 v232, v232, v12, s79
	v_add3_u32 v234, v234, v14, s79
	v_add3_u32 v229, v229, v9, s79
	v_add3_u32 v231, v231, v11, s79
	v_add3_u32 v233, v233, v13, s79
	v_add3_u32 v235, v235, v15, s79
	v_lshrrev_b32_e32 v228, 16, v228
	v_lshrrev_b32_e32 v230, 16, v230
	v_lshrrev_b32_e32 v232, 16, v232
	v_lshrrev_b32_e32 v234, 16, v234
	v_and_or_b32 v228, v229, s80, v228
	v_and_or_b32 v229, v231, s80, v230
	v_and_or_b32 v230, v233, s80, v232
	v_and_or_b32 v231, v235, s80, v234
	s_and_b64 exec, s[12:13], s[20:21]
	v_add_u32_e32 v4, v106, v110
	ds_write_b128 v4, v[228:231]
	s_mov_b64 exec, s[12:13]
	s_mov_b64 s[0:1], 0
